# in-projection epilogue: cross-lane sums with v_permlane16/32_swap instead of ds_bpermute round trips, argument pointers from register lanes instead of scalar loads
# speedup vs baseline: 1.1174x; 1.0016x over previous
; DI int get_tid() { int t = threadIdx.x; asm volatile("" : "+v"(t)); return t; }
; DI void phaseA_tile(const Params& p0, int l, int ft, int mt, char* lds) {
;     ...
;   Params p; reload_params(p);
;   const int n0 = ft * 256, m0 = mt * 256;
;   const int tid = get_tid(), lane = tid & 63, wid = tid >> 6, wr = wid >> 2, wc = wid & 3, fr = lane & 15, fq = lane >> 4;
;   const bool is_ctx = m0 >= NLAT;
;   int b, s_base, modrow;
;   if (!is_ctx) { b = m0 / SEQ; s_base = m0 % SEQ; modrow = b; }
;   else { const int c = m0 - NLAT; b = c / CTX; s_base = c % CTX; modrow = 16; }
;   int tl[4];
; #pragma unroll
;   for (int g = 0; g < 4; ++g) tl[g] = (g >> 1) * 128 + wc * 32 + (g & 1) * 16 + fr;
;   f32x4 bvA[2][4];
;   {
;     const float* bb = p.bias + (size_t)(l * 17 + modrow) * INW + n0 + wr * 64 + fq * 4;
; #pragma unroll
;     for (int ai = 0; ai < 2; ++ai)
; #pragma unroll
;       for (int m = 0; m < 4; ++m) bvA[ai][m] = *(const f32x4*)(bb + ai * 128 + m * 16);
;   }
;   float rstd[4];
; #pragma unroll
;   for (int gp = 0; gp < 2; ++gp) {
;     f32x4 sq[2][4];
; #pragma unroll
;     for (int n = 0; n < 2; ++n) {
;       const f32x4* sp = (const f32x4*)(p.ssq + (size_t)(m0 + tl[gp * 2 + n]) * 16);
; #pragma unroll
;       for (int q = 0; q < 4; ++q) sq[n][q] = sp[q];
;     }
; #pragma unroll
;     for (int n = 0; n < 2; ++n) {
;       float ss = 0.f;
; #pragma unroll
;       for (int q = 0; q < 4; ++q) ss += (sq[n][q][0] + sq[n][q][1]) + (sq[n][q][2] + sq[n][q][3]);
;       rstd[gp * 2 + n] = rsqrtf(ss * (1.f / DM) + EPS);
;     }
;   }
.LBB0_356:
	s_or_b64 exec, exec, s[2:3]
	v_readlane_b32 s38, v255, 3
	s_barrier
	v_readlane_b32 s8, v254, 49
	v_readlane_b32 s9, v254, 50
	v_readlane_b32 s10, v254, 51
	v_readlane_b32 s11, v254, 52
	v_readlane_b32 s34, v254, 53
	v_readlane_b32 s35, v254, 54
	v_readlane_b32 s6, v254, 57
	v_readlane_b32 s7, v254, 58
	s_lshl_b32 s0, s28, 8
	s_lshl_b32 s30, s68, 8
	s_lshr_b32 s2, s28, 3
	s_sub_i32 s3, s28, 0x80
	s_and_b32 s69, s28, 7
	s_lshl_b32 s69, s69, 8
	s_cmpk_lt_i32 s28, 0x80
	s_cselect_b32 s39, s2, s3
	s_cselect_b32 s2, s2, 16
	s_cselect_b32 s69, s69, 0
	s_cselect_b32 s74, 0, 0x800
	s_cselect_b32 s42, 1, 0
	s_lshl_b32 s3, 1, s68
	s_mov_b32 s40, 1
	s_mov_b32 s41, 1
	s_and_b32 s70, s3, 0x187
	s_cselect_b32 s40, 2, s40
	s_and_b32 s70, s3, 0x200
	s_cselect_b32 s40, 3, s40
	s_and_b32 s70, s3, 0x20
	s_cselect_b32 s40, 0, s40
	s_and_b32 s70, s3, 0x183
	s_cselect_b32 s41, 2, s41
	s_and_b32 s70, s3, 0x204
	s_cselect_b32 s41, 3, s41
	s_and_b32 s70, s3, 0x20
	s_cselect_b32 s41, 0, s41
	s_and_b32 s70, s3, 0x7
	s_cselect_b32 s42, s42, 0
	s_mov_b32 s43, 1.0
	s_and_b32 s70, s3, 0x83
	s_cselect_b32 s43, 0x3e38aa3b, s43
	s_waitcnt lgkmcnt(0)
	s_lshl_b32 s2, s69, 1
	s_add_u32 s46, s6, s2
	s_addc_u32 s47, s7, 0
	v_and_b32_e32 v114, 15, v251
	v_bfe_u32 v115, v251, 4, 2
	v_bfe_u32 v116, v251, 6, 2
	v_lshrrev_b32_e32 v117, 8, v251
	v_lshlrev_b32_e32 v140, 4, v115
	v_lshl_add_u32 v137, v117, 8, v140
	v_add_u32_e32 v137, 0x21e40, v137
	v_lshl_add_u32 v118, v116, 5, v114
	v_lshl_add_u32 v138, v118, 6, v140
	v_add_u32_e32 v138, 0x22340, v138
	v_add_u32_e32 v140, 0x22240, v140
	v_lshrrev_b32_e32 v119, 1, v116
	v_lshlrev_b32_e32 v120, 5, v115
	v_lshl_add_u32 v141, v119, 7, v120
	v_and_b32_e32 v119, 1, v116
	v_lshl_add_u32 v119, v119, 5, v114
	v_lshl_add_u32 v142, v119, 7, v120
	v_lshrrev_b32_e32 v119, 1, v115
	v_lshl_or_b32 v119, v117, 3, v119
	v_xor_b32_e32 v119, v119, v114
	v_lshlrev_b32_e32 v119, 4, v119
	v_and_b32_e32 v120, 1, v115
	v_lshl_or_b32 v119, v120, 3, v119
	v_lshl_add_u32 v130, v118, 9, v119
	v_xor_b32_e32 v131, 32, v130
	v_xor_b32_e32 v132, 64, v130
	v_xor_b32_e32 v133, 96, v130
	v_and_b32_e32 v119, 3, v114
	v_and_b32_e32 v120, 4, v114
	v_lshl_or_b32 v119, v120, 1, v119
	v_and_b32_e32 v120, 8, v114
	v_lshrrev_b32_e32 v120, 1, v120
	v_or_b32_e32 v119, v119, v120
	v_lshl_add_u32 v119, v116, 5, v119
	v_lshlrev_b32_e32 v119, 1, v119
	v_mul_u32_u24_e32 v120, 0x4800, v115
	v_mul_u32_u24_e32 v121, 0x48000, v117
	v_add3_u32 v134, v119, v120, v121
	v_xor_b32_e32 v135, 16, v240
	v_lshlrev_b32_e32 v135, 2, v135
	v_xor_b32_e32 v136, 32, v240
	v_lshlrev_b32_e32 v136, 2, v136
	ds_read_b128 v[34:37], v137 offset:0
	ds_read_b128 v[38:41], v137 offset:64
	ds_read_b128 v[42:45], v137 offset:128
	ds_read_b128 v[46:49], v137 offset:192
	ds_read_b128 v[146:149], v137 offset:512
	ds_read_b128 v[150:153], v137 offset:576
	ds_read_b128 v[154:157], v137 offset:640
	ds_read_b128 v[158:161], v137 offset:704
	ds_read_b128 v[114:117], v138 offset:0
	ds_read_b128 v[118:121], v138 offset:1024
	ds_read_b128 v[122:125], v138 offset:8192
	ds_read_b128 v[126:129], v138 offset:9216
	ds_read_b128 v[194:197], v140
	ds_read_b128 v[198:201], v140 offset:64
	ds_read_b128 v[202:205], v140 offset:128
	ds_read_b128 v[206:209], v140 offset:192
	global_load_dwordx4 v[210:213], v141, s[46:47] offset:0
	global_load_dwordx4 v[214:217], v141, s[46:47] offset:16
	global_load_dwordx4 v[218:221], v141, s[46:47] offset:256
	global_load_dwordx4 v[222:225], v141, s[46:47] offset:272
	global_load_dwordx4 v[226:229], v142, s[6:7] offset:0
	global_load_dwordx4 v[230:233], v142, s[6:7] offset:16
	global_load_dwordx4 v[234:237], v142, s[6:7] offset:2048
	global_load_dwordx4 v[242:245], v142, s[6:7] offset:2064
	s_waitcnt lgkmcnt(0)
	v_add_f32_e32 v114, v114, v115
	v_add_f32_e32 v116, v116, v117
	v_add_f32_e32 v118, v118, v119
	v_add_f32_e32 v120, v120, v121
	v_add_f32_e32 v122, v122, v123
	v_add_f32_e32 v124, v124, v125
	v_add_f32_e32 v126, v126, v127
	v_add_f32_e32 v128, v128, v129
	v_add_f32_e32 v143, v114, v116
	v_add_f32_e32 v144, v118, v120
	v_add_f32_e32 v145, v122, v124
	v_add_f32_e32 v239, v126, v128
	v_mov_b32_e32 v114, v143
	v_mov_b32_e32 v115, v144
	v_mov_b32_e32 v116, v145
	v_mov_b32_e32 v117, v239
	s_nop 1
	v_permlane16_swap_b32 v143, v114
	v_permlane16_swap_b32 v144, v115
	v_permlane16_swap_b32 v145, v116
	v_permlane16_swap_b32 v239, v117
	v_add_f32_e32 v143, v143, v114
	v_add_f32_e32 v144, v144, v115
	v_add_f32_e32 v145, v145, v116
	v_add_f32_e32 v239, v239, v117
	s_nop 0
	v_mov_b32_e32 v114, v143
	v_mov_b32_e32 v115, v144
	v_mov_b32_e32 v116, v145
	v_mov_b32_e32 v117, v239
	s_nop 1
	v_permlane32_swap_b32 v143, v114
	v_permlane32_swap_b32 v144, v115
	v_permlane32_swap_b32 v145, v116
	v_permlane32_swap_b32 v239, v117
	v_add_f32_e32 v143, v143, v114
	v_add_f32_e32 v144, v144, v115
	v_add_f32_e32 v145, v145, v116
	v_add_f32_e32 v239, v239, v117
	s_nop 0
	v_mov_b32_e32 v118, 0x358637bd
	s_mov_b32 s2, 0x3a800000
	s_mov_b32 s3, 0x800000
	v_fma_f32 v143, v143, s2, v118
	v_fma_f32 v144, v144, s2, v118
	v_fma_f32 v145, v145, s2, v118
	v_fma_f32 v239, v239, s2, v118
	v_mul_f32_e32 v119, 0x4b800000, v143
	v_cmp_gt_f32_e32 vcc, s3, v143
	s_nop 1
	v_cndmask_b32_e32 v119, v143, v119, vcc
	v_rsq_f32_e32 v119, v119
	s_nop 0
	v_mul_f32_e32 v0, 0x45800000, v119
	v_cndmask_b32_e32 v0, v119, v0, vcc
	v_mul_f32_e32 v120, 0x4b800000, v144
	v_cmp_gt_f32_e32 vcc, s3, v144
	s_nop 1
	v_cndmask_b32_e32 v120, v144, v120, vcc
	v_rsq_f32_e32 v120, v120
	s_nop 0
	v_mul_f32_e32 v238, 0x45800000, v120
	v_cndmask_b32_e32 v238, v120, v238, vcc
	v_mul_f32_e32 v121, 0x4b800000, v145
	v_cmp_gt_f32_e32 vcc, s3, v145
	s_nop 1
; DI float silu_f(float v) { return v * __builtin_amdgcn_rcpf(1.f + __expf(-v)); }
; DI void phaseA_tile(const Params& p0, int l, int ft, int mt, char* lds) {
;     ...
;       rstd[gp * 2 + n] = rsqrtf(ss * (1.f / DM) + EPS);
;     }
;   }
; #pragma unroll
;   for (int ai = 0; ai < 2; ++ai) {
;     const int f0 = n0 + ai * 128 + wr * 64;
;     const int hd = f0 >> 6;
;     int kind = 0; const float* gain = p.att_q_gain; bool do_rope = false; bool do_scale = false;
;     bf16_t* vtb = nullptr;
;     if (hd < 8) { kind = 2; gain = p.att_q_gain + l * 64; do_rope = !is_ctx; do_scale = true; }
;     else if (hd < 10) { kind = 2; gain = p.att_k_gain + l * 64; do_rope = !is_ctx; }
;     else if (hd < 12) { kind = 3; vtb = p.VtA + (size_t)((b * 2 + (hd - 10)) * 64) * KEYS; }
;     else if (hd < 20) { kind = 1; }
;     else if (hd < 24) { kind = 0; }
;     else if (hd < 28) { kind = 1; }
;     else if (hd < 32) { kind = 2; gain = p.na_q_gain + l * 64; do_scale = true; }
;     else if (hd < 36) { kind = 2; gain = p.na_k_gain + l * 64; }
;     else if (hd < 40) { kind = 3; vtb = p.VtN + (size_t)((b * 4 + (hd - 36)) * 64) * KEYS; }
;     else { kind = 1; }
;     f32x4 bv[4];
; #pragma unroll
;     for (int m = 0; m < 4; ++m) bv[m] = bvA[ai][m];
;     const float sc = do_scale ? 0.125f * LOG2E : 1.f;
; #pragma unroll
;     for (int gp = 0; gp < 2; ++gp) {
;       float v[2][4][4];
; #pragma unroll
;       for (int n = 0; n < 2; ++n)
; #pragma unroll
;         for (int m = 0; m < 4; ++m)
; #pragma unroll
;           for (int j = 0; j < 4; ++j) v[n][m][j] = acc[ai][gp][m][n][j] * rstd[gp * 2 + n] + bv[m][j];
;       if (kind == 1) {
; #pragma unroll
;         for (int n = 0; n < 2; ++n)
; #pragma unroll
;           for (int m = 0; m < 4; ++m)
; #pragma unroll
;             for (int j = 0; j < 4; ++j) v[n][m][j] = silu_f(v[n][m][j]);
	v_cndmask_b32_e32 v121, v145, v121, vcc
	v_rsq_f32_e32 v121, v121
	s_nop 0
	v_mul_f32_e32 v246, 0x45800000, v121
	v_cndmask_b32_e32 v246, v121, v246, vcc
	v_mul_f32_e32 v122, 0x4b800000, v239
	v_cmp_gt_f32_e32 vcc, s3, v239
	s_nop 1
	v_cndmask_b32_e32 v122, v239, v122, vcc
	v_rsq_f32_e32 v122, v122
	s_nop 0
	v_mul_f32_e32 v248, 0x45800000, v122
	v_cndmask_b32_e32 v248, v122, v248, vcc
	s_mov_b32 s70, 0xbfb8aa3b
	s_mov_b32 s71, 1.0
	v_pk_fma_f32 v[190:191], v[190:191], v[0:1], v[34:35] op_sel_hi:[1,0,1]
	v_pk_fma_f32 v[192:193], v[192:193], v[0:1], v[36:37] op_sel_hi:[1,0,1]
	v_pk_fma_f32 v[186:187], v[186:187], v[0:1], v[38:39] op_sel_hi:[1,0,1]
	v_pk_fma_f32 v[188:189], v[188:189], v[0:1], v[40:41] op_sel_hi:[1,0,1]
	v_pk_fma_f32 v[178:179], v[178:179], v[0:1], v[42:43] op_sel_hi:[1,0,1]
	v_pk_fma_f32 v[180:181], v[180:181], v[0:1], v[44:45] op_sel_hi:[1,0,1]
	v_pk_fma_f32 v[170:171], v[170:171], v[0:1], v[46:47] op_sel_hi:[1,0,1]
	v_pk_fma_f32 v[172:173], v[172:173], v[0:1], v[48:49] op_sel_hi:[1,0,1]
	v_pk_fma_f32 v[182:183], v[182:183], v[238:239], v[34:35] op_sel_hi:[1,0,1]
	v_pk_fma_f32 v[184:185], v[184:185], v[238:239], v[36:37] op_sel_hi:[1,0,1]
	v_pk_fma_f32 v[174:175], v[174:175], v[238:239], v[38:39] op_sel_hi:[1,0,1]
	v_pk_fma_f32 v[176:177], v[176:177], v[238:239], v[40:41] op_sel_hi:[1,0,1]
	v_pk_fma_f32 v[166:167], v[166:167], v[238:239], v[42:43] op_sel_hi:[1,0,1]
	v_pk_fma_f32 v[168:169], v[168:169], v[238:239], v[44:45] op_sel_hi:[1,0,1]
	v_pk_fma_f32 v[162:163], v[162:163], v[238:239], v[46:47] op_sel_hi:[1,0,1]
	v_pk_fma_f32 v[164:165], v[164:165], v[238:239], v[48:49] op_sel_hi:[1,0,1]
	s_cmp_eq_u32 s40, 1
	s_cbranch_scc0 .Lea_n1_00
	v_pk_mul_f32 v[114:115], v[190:191], s[70:71] op_sel_hi:[1,0]
	v_pk_mul_f32 v[116:117], v[192:193], s[70:71] op_sel_hi:[1,0]
	v_pk_mul_f32 v[118:119], v[186:187], s[70:71] op_sel_hi:[1,0]
	v_pk_mul_f32 v[120:121], v[188:189], s[70:71] op_sel_hi:[1,0]
	v_exp_f32_e32 v114, v114
	v_exp_f32_e32 v115, v115
	v_exp_f32_e32 v116, v116
	v_exp_f32_e32 v117, v117
	v_exp_f32_e32 v118, v118
	v_exp_f32_e32 v119, v119
	v_exp_f32_e32 v120, v120
	v_exp_f32_e32 v121, v121
	v_pk_add_f32 v[114:115], v[114:115], s[70:71] op_sel:[0,1] op_sel_hi:[1,1]
	v_pk_add_f32 v[116:117], v[116:117], s[70:71] op_sel:[0,1] op_sel_hi:[1,1]
	v_pk_add_f32 v[118:119], v[118:119], s[70:71] op_sel:[0,1] op_sel_hi:[1,1]
	v_pk_add_f32 v[120:121], v[120:121], s[70:71] op_sel:[0,1] op_sel_hi:[1,1]
	v_rcp_f32_e32 v114, v114
	v_rcp_f32_e32 v115, v115
	v_rcp_f32_e32 v116, v116
	v_rcp_f32_e32 v117, v117
	v_rcp_f32_e32 v118, v118
	v_rcp_f32_e32 v119, v119
	v_rcp_f32_e32 v120, v120
	v_rcp_f32_e32 v121, v121
	s_nop 0
	v_pk_mul_f32 v[190:191], v[190:191], v[114:115]
	v_pk_mul_f32 v[192:193], v[192:193], v[116:117]
	v_pk_mul_f32 v[186:187], v[186:187], v[118:119]
	v_pk_mul_f32 v[188:189], v[188:189], v[120:121]
	v_pk_mul_f32 v[114:115], v[178:179], s[70:71] op_sel_hi:[1,0]
	v_pk_mul_f32 v[116:117], v[180:181], s[70:71] op_sel_hi:[1,0]
	v_pk_mul_f32 v[118:119], v[170:171], s[70:71] op_sel_hi:[1,0]
	v_pk_mul_f32 v[120:121], v[172:173], s[70:71] op_sel_hi:[1,0]
	v_exp_f32_e32 v114, v114
	v_exp_f32_e32 v115, v115
	v_exp_f32_e32 v116, v116
	v_exp_f32_e32 v117, v117
	v_exp_f32_e32 v118, v118
	v_exp_f32_e32 v119, v119
	v_exp_f32_e32 v120, v120
	v_exp_f32_e32 v121, v121
	v_pk_add_f32 v[114:115], v[114:115], s[70:71] op_sel:[0,1] op_sel_hi:[1,1]
	v_pk_add_f32 v[116:117], v[116:117], s[70:71] op_sel:[0,1] op_sel_hi:[1,1]
	v_pk_add_f32 v[118:119], v[118:119], s[70:71] op_sel:[0,1] op_sel_hi:[1,1]
	v_pk_add_f32 v[120:121], v[120:121], s[70:71] op_sel:[0,1] op_sel_hi:[1,1]
	v_rcp_f32_e32 v114, v114
	v_rcp_f32_e32 v115, v115
	v_rcp_f32_e32 v116, v116
	v_rcp_f32_e32 v117, v117
	v_rcp_f32_e32 v118, v118
	v_rcp_f32_e32 v119, v119
	v_rcp_f32_e32 v120, v120
	v_rcp_f32_e32 v121, v121
	s_nop 0
	v_pk_mul_f32 v[178:179], v[178:179], v[114:115]
	v_pk_mul_f32 v[180:181], v[180:181], v[116:117]
	v_pk_mul_f32 v[170:171], v[170:171], v[118:119]
	v_pk_mul_f32 v[172:173], v[172:173], v[120:121]
	v_pk_mul_f32 v[114:115], v[182:183], s[70:71] op_sel_hi:[1,0]
	v_pk_mul_f32 v[116:117], v[184:185], s[70:71] op_sel_hi:[1,0]
	v_pk_mul_f32 v[118:119], v[174:175], s[70:71] op_sel_hi:[1,0]
	v_pk_mul_f32 v[120:121], v[176:177], s[70:71] op_sel_hi:[1,0]
	v_exp_f32_e32 v114, v114
	v_exp_f32_e32 v115, v115
	v_exp_f32_e32 v116, v116
	v_exp_f32_e32 v117, v117
	v_exp_f32_e32 v118, v118
	v_exp_f32_e32 v119, v119
	v_exp_f32_e32 v120, v120
	v_exp_f32_e32 v121, v121
	v_pk_add_f32 v[114:115], v[114:115], s[70:71] op_sel:[0,1] op_sel_hi:[1,1]
	v_pk_add_f32 v[116:117], v[116:117], s[70:71] op_sel:[0,1] op_sel_hi:[1,1]
	v_pk_add_f32 v[118:119], v[118:119], s[70:71] op_sel:[0,1] op_sel_hi:[1,1]
	v_pk_add_f32 v[120:121], v[120:121], s[70:71] op_sel:[0,1] op_sel_hi:[1,1]
	v_rcp_f32_e32 v114, v114
	v_rcp_f32_e32 v115, v115
	v_rcp_f32_e32 v116, v116
	v_rcp_f32_e32 v117, v117
	v_rcp_f32_e32 v118, v118
	v_rcp_f32_e32 v119, v119
	v_rcp_f32_e32 v120, v120
	v_rcp_f32_e32 v121, v121
	s_nop 0
	v_pk_mul_f32 v[182:183], v[182:183], v[114:115]
	v_pk_mul_f32 v[184:185], v[184:185], v[116:117]
	v_pk_mul_f32 v[174:175], v[174:175], v[118:119]
	v_pk_mul_f32 v[176:177], v[176:177], v[120:121]
	v_pk_mul_f32 v[114:115], v[166:167], s[70:71] op_sel_hi:[1,0]
	v_pk_mul_f32 v[116:117], v[168:169], s[70:71] op_sel_hi:[1,0]
	v_pk_mul_f32 v[118:119], v[162:163], s[70:71] op_sel_hi:[1,0]
	v_pk_mul_f32 v[120:121], v[164:165], s[70:71] op_sel_hi:[1,0]
	v_exp_f32_e32 v114, v114
	v_exp_f32_e32 v115, v115
	v_exp_f32_e32 v116, v116
	v_exp_f32_e32 v117, v117
	v_exp_f32_e32 v118, v118
	v_exp_f32_e32 v119, v119
	v_exp_f32_e32 v120, v120
	v_exp_f32_e32 v121, v121
	v_pk_add_f32 v[114:115], v[114:115], s[70:71] op_sel:[0,1] op_sel_hi:[1,1]
	v_pk_add_f32 v[116:117], v[116:117], s[70:71] op_sel:[0,1] op_sel_hi:[1,1]
	v_pk_add_f32 v[118:119], v[118:119], s[70:71] op_sel:[0,1] op_sel_hi:[1,1]
	v_pk_add_f32 v[120:121], v[120:121], s[70:71] op_sel:[0,1] op_sel_hi:[1,1]
	v_rcp_f32_e32 v114, v114
	v_rcp_f32_e32 v115, v115
	v_rcp_f32_e32 v116, v116
	v_rcp_f32_e32 v117, v117
	v_rcp_f32_e32 v118, v118
	v_rcp_f32_e32 v119, v119
	v_rcp_f32_e32 v120, v120
	v_rcp_f32_e32 v121, v121
	s_nop 0
	v_pk_mul_f32 v[166:167], v[166:167], v[114:115]
	v_pk_mul_f32 v[168:169], v[168:169], v[116:117]
	v_pk_mul_f32 v[162:163], v[162:163], v[118:119]
	v_pk_mul_f32 v[164:165], v[164:165], v[120:121]
	s_branch .Lea_pack_00
; DI void phaseA_tile(const Params& p0, int l, int ft, int mt, char* lds) {
;     ...
;       } else if (kind == 2) {
;         f32x4 gv[4];
; #pragma unroll
;         for (int m = 0; m < 4; ++m) gv[m] = *(const f32x4*)(gain + m * 16 + fq * 4);
; #pragma unroll
;         for (int n = 0; n < 2; ++n) {
;           float ss = 0.f;
; #pragma unroll
;           for (int m = 0; m < 4; ++m)
; #pragma unroll
;             for (int j = 0; j < 4; ++j) ss += v[n][m][j] * v[n][m][j];
;           ss += __shfl_xor(ss, 16);
;           ss += __shfl_xor(ss, 32);
;           const float rn = rsqrtf(ss * (1.f / 64.f) + EPS) * sc;
; #pragma unroll
;           for (int m = 0; m < 4; ++m)
; #pragma unroll
;             for (int j = 0; j < 4; ++j) v[n][m][j] *= rn * gv[m][j];
;         }
;         if (do_rope) {
; #pragma unroll
;           for (int n = 0; n < 2; ++n) {
;             f32x4 cs4[2][2];
;             const int s = s_base + tl[gp * 2 + n];
; #pragma unroll
;             for (int hf = 0; hf < 2; ++hf) {
;               const int pos = hf == 0 ? (s >> 6) : (s & 63);
;               const float* tb = p.rope + (size_t)pos * 32 + fq * 8;
;               cs4[hf][0] = *(const f32x4*)(tb);
;               cs4[hf][1] = *(const f32x4*)(tb + 4);
;             }
; #pragma unroll
;             for (int hf = 0; hf < 2; ++hf)
; #pragma unroll
;               for (int j = 0; j < 4; ++j) {
;                 const float c = cs4[hf][j >> 1][(j & 1) * 2], sn = cs4[hf][j >> 1][(j & 1) * 2 + 1];
;                 const float x1 = v[n][2 * hf][j], x2 = v[n][2 * hf + 1][j];
;                 v[n][2 * hf][j] = x1 * c - x2 * sn;
;                 v[n][2 * hf + 1][j] = x2 * c + x1 * sn;
;               }
;           }
;         }
.Lea_n1_00:
	s_cmp_eq_u32 s40, 2
	s_cbranch_scc0 .Lea_n2_00
	v_pk_mul_f32 v[114:115], v[190:191], v[190:191]
	v_pk_fma_f32 v[114:115], v[192:193], v[192:193], v[114:115]
	v_pk_fma_f32 v[114:115], v[186:187], v[186:187], v[114:115]
	v_pk_fma_f32 v[114:115], v[188:189], v[188:189], v[114:115]
	v_pk_fma_f32 v[114:115], v[178:179], v[178:179], v[114:115]
	v_pk_fma_f32 v[114:115], v[180:181], v[180:181], v[114:115]
	v_pk_fma_f32 v[114:115], v[170:171], v[170:171], v[114:115]
	v_pk_fma_f32 v[114:115], v[172:173], v[172:173], v[114:115]
	v_pk_mul_f32 v[116:117], v[182:183], v[182:183]
	v_pk_fma_f32 v[116:117], v[184:185], v[184:185], v[116:117]
	v_pk_fma_f32 v[116:117], v[174:175], v[174:175], v[116:117]
	v_pk_fma_f32 v[116:117], v[176:177], v[176:177], v[116:117]
	v_pk_fma_f32 v[116:117], v[166:167], v[166:167], v[116:117]
	v_pk_fma_f32 v[116:117], v[168:169], v[168:169], v[116:117]
	v_pk_fma_f32 v[116:117], v[162:163], v[162:163], v[116:117]
	v_pk_fma_f32 v[116:117], v[164:165], v[164:165], v[116:117]
	v_add_f32_e32 v114, v114, v115
	v_add_f32_e32 v116, v116, v117
	v_mov_b32_e32 v118, v114
	v_mov_b32_e32 v119, v116
	s_nop 1
	v_permlane16_swap_b32 v114, v118
	v_permlane16_swap_b32 v116, v119
	v_add_f32_e32 v114, v114, v118
	v_add_f32_e32 v116, v116, v119
	s_nop 0
	v_mov_b32_e32 v118, v114
	v_mov_b32_e32 v119, v116
	s_nop 1
	v_permlane32_swap_b32 v114, v118
	v_permlane32_swap_b32 v116, v119
	v_add_f32_e32 v114, v114, v118
	v_add_f32_e32 v116, v116, v119
	s_nop 0
	v_mov_b32_e32 v120, 0x358637bd
	s_mov_b32 s2, 0x3c800000
	v_fma_f32 v114, v114, s2, v120
	v_fma_f32 v116, v116, s2, v120
	v_mul_f32_e32 v118, 0x4b800000, v114
	v_cmp_gt_f32_e32 vcc, s3, v114
	s_nop 1
	v_cndmask_b32_e32 v118, v114, v118, vcc
	v_rsq_f32_e32 v118, v118
	s_nop 0
	v_mul_f32_e32 v122, 0x45800000, v118
	v_cndmask_b32_e32 v122, v118, v122, vcc
	v_mul_f32_e32 v119, 0x4b800000, v116
	v_cmp_gt_f32_e32 vcc, s3, v116
	s_nop 1
	v_cndmask_b32_e32 v119, v116, v119, vcc
	v_rsq_f32_e32 v119, v119
	s_nop 0
	v_mul_f32_e32 v124, 0x45800000, v119
	v_cndmask_b32_e32 v124, v119, v124, vcc
	v_mul_f32_e32 v122, s43, v122
	v_mul_f32_e32 v124, s43, v124
	v_pk_mul_f32 v[126:127], v[194:195], v[122:123] op_sel_hi:[1,0]
	v_pk_mul_f32 v[190:191], v[190:191], v[126:127]
	v_pk_mul_f32 v[126:127], v[196:197], v[122:123] op_sel_hi:[1,0]
	v_pk_mul_f32 v[192:193], v[192:193], v[126:127]
	v_pk_mul_f32 v[126:127], v[198:199], v[122:123] op_sel_hi:[1,0]
	v_pk_mul_f32 v[186:187], v[186:187], v[126:127]
	v_pk_mul_f32 v[126:127], v[200:201], v[122:123] op_sel_hi:[1,0]
	v_pk_mul_f32 v[188:189], v[188:189], v[126:127]
	v_pk_mul_f32 v[126:127], v[202:203], v[122:123] op_sel_hi:[1,0]
	v_pk_mul_f32 v[178:179], v[178:179], v[126:127]
	v_pk_mul_f32 v[126:127], v[204:205], v[122:123] op_sel_hi:[1,0]
	v_pk_mul_f32 v[180:181], v[180:181], v[126:127]
	v_pk_mul_f32 v[126:127], v[206:207], v[122:123] op_sel_hi:[1,0]
	v_pk_mul_f32 v[170:171], v[170:171], v[126:127]
	v_pk_mul_f32 v[126:127], v[208:209], v[122:123] op_sel_hi:[1,0]
	v_pk_mul_f32 v[172:173], v[172:173], v[126:127]
	v_pk_mul_f32 v[126:127], v[194:195], v[124:125] op_sel_hi:[1,0]
	v_pk_mul_f32 v[182:183], v[182:183], v[126:127]
	v_pk_mul_f32 v[126:127], v[196:197], v[124:125] op_sel_hi:[1,0]
	v_pk_mul_f32 v[184:185], v[184:185], v[126:127]
	v_pk_mul_f32 v[126:127], v[198:199], v[124:125] op_sel_hi:[1,0]
	v_pk_mul_f32 v[174:175], v[174:175], v[126:127]
	v_pk_mul_f32 v[126:127], v[200:201], v[124:125] op_sel_hi:[1,0]
	v_pk_mul_f32 v[176:177], v[176:177], v[126:127]
	v_pk_mul_f32 v[126:127], v[202:203], v[124:125] op_sel_hi:[1,0]
	v_pk_mul_f32 v[166:167], v[166:167], v[126:127]
	v_pk_mul_f32 v[126:127], v[204:205], v[124:125] op_sel_hi:[1,0]
	v_pk_mul_f32 v[168:169], v[168:169], v[126:127]
	v_pk_mul_f32 v[126:127], v[206:207], v[124:125] op_sel_hi:[1,0]
	v_pk_mul_f32 v[162:163], v[162:163], v[126:127]
	v_pk_mul_f32 v[126:127], v[208:209], v[124:125] op_sel_hi:[1,0]
	v_pk_mul_f32 v[164:165], v[164:165], v[126:127]
	s_cmp_eq_u32 s42, 0
	s_cbranch_scc1 .Lea_pack_00
	s_waitcnt vmcnt(0)
	v_mul_f32_e32 v126, v186, v211
	v_mul_f32_e32 v127, v190, v211
	v_fma_f32 v190, v190, v210, -v126
	v_fma_f32 v186, v186, v210, v127
	v_mul_f32_e32 v126, v187, v213
	v_mul_f32_e32 v127, v191, v213
	v_fma_f32 v191, v191, v212, -v126
	v_fma_f32 v187, v187, v212, v127
	v_mul_f32_e32 v126, v188, v215
	v_mul_f32_e32 v127, v192, v215
	v_fma_f32 v192, v192, v214, -v126
	v_fma_f32 v188, v188, v214, v127
	v_mul_f32_e32 v126, v189, v217
	v_mul_f32_e32 v127, v193, v217
	v_fma_f32 v193, v193, v216, -v126
	v_fma_f32 v189, v189, v216, v127
	v_mul_f32_e32 v126, v170, v227
	v_mul_f32_e32 v127, v178, v227
	v_fma_f32 v178, v178, v226, -v126
	v_fma_f32 v170, v170, v226, v127
	v_mul_f32_e32 v126, v171, v229
	v_mul_f32_e32 v127, v179, v229
	v_fma_f32 v179, v179, v228, -v126
	v_fma_f32 v171, v171, v228, v127
	v_mul_f32_e32 v126, v172, v231
	v_mul_f32_e32 v127, v180, v231
	v_fma_f32 v180, v180, v230, -v126
	v_fma_f32 v172, v172, v230, v127
	v_mul_f32_e32 v126, v173, v233
	v_mul_f32_e32 v127, v181, v233
	v_fma_f32 v181, v181, v232, -v126
	v_fma_f32 v173, v173, v232, v127
	v_mul_f32_e32 v126, v174, v211
	v_mul_f32_e32 v127, v182, v211
	v_fma_f32 v182, v182, v210, -v126
	v_fma_f32 v174, v174, v210, v127
	v_mul_f32_e32 v126, v175, v213
	v_mul_f32_e32 v127, v183, v213
	v_fma_f32 v183, v183, v212, -v126
	v_fma_f32 v175, v175, v212, v127
	v_mul_f32_e32 v126, v176, v215
	v_mul_f32_e32 v127, v184, v215
	v_fma_f32 v184, v184, v214, -v126
	v_fma_f32 v176, v176, v214, v127
	v_mul_f32_e32 v126, v177, v217
	v_mul_f32_e32 v127, v185, v217
	v_fma_f32 v185, v185, v216, -v126
	v_fma_f32 v177, v177, v216, v127
	v_mul_f32_e32 v126, v162, v235
	v_mul_f32_e32 v127, v166, v235
	v_fma_f32 v166, v166, v234, -v126
	v_fma_f32 v162, v162, v234, v127
	v_mul_f32_e32 v126, v163, v237
	v_mul_f32_e32 v127, v167, v237
	v_fma_f32 v167, v167, v236, -v126
	v_fma_f32 v163, v163, v236, v127
	v_mul_f32_e32 v126, v164, v243
	v_mul_f32_e32 v127, v168, v243
	v_fma_f32 v168, v168, v242, -v126
	v_fma_f32 v164, v164, v242, v127
	v_mul_f32_e32 v126, v165, v245
	v_mul_f32_e32 v127, v169, v245
	v_fma_f32 v169, v169, v244, -v126
	v_fma_f32 v165, v165, v244, v127
	s_branch .Lea_pack_00

; DI void phaseA_tile(const Params& p0, int l, int ft, int mt, char* lds) {
;     ...
;         for (int n = 0; n < 2; ++n) {
;           float ss = 0.f;
; #pragma unroll
;           for (int m = 0; m < 4; ++m)
; #pragma unroll
;             for (int j = 0; j < 4; ++j) ss += v[n][m][j] * v[n][m][j];
;           ss += __shfl_xor(ss, 16);
;           ss += __shfl_xor(ss, 32);
;           const float rn = rsqrtf(ss * (1.f / 64.f) + EPS) * sc;
; #pragma unroll
;           for (int m = 0; m < 4; ++m)
; #pragma unroll
;             for (int j = 0; j < 4; ++j) v[n][m][j] *= rn * gv[m][j];
;         }
;         if (do_rope) {
; #pragma unroll
;           for (int n = 0; n < 2; ++n) {
;             f32x4 cs4[2][2];
;             const int s = s_base + tl[gp * 2 + n];
; #pragma unroll
;             for (int hf = 0; hf < 2; ++hf) {
;               const int pos = hf == 0 ? (s >> 6) : (s & 63);
;               const float* tb = p.rope + (size_t)pos * 32 + fq * 8;
;               cs4[hf][0] = *(const f32x4*)(tb);
;               cs4[hf][1] = *(const f32x4*)(tb + 4);
;             }
; #pragma unroll
;             for (int hf = 0; hf < 2; ++hf)
; #pragma unroll
;               for (int j = 0; j < 4; ++j) {
;                 const float c = cs4[hf][j >> 1][(j & 1) * 2], sn = cs4[hf][j >> 1][(j & 1) * 2 + 1];
;                 const float x1 = v[n][2 * hf][j], x2 = v[n][2 * hf + 1][j];
;                 v[n][2 * hf][j] = x1 * c - x2 * sn;
;                 v[n][2 * hf + 1][j] = x2 * c + x1 * sn;
;               }
;           }
;         }
.Lea_n1_10:
	s_cmp_eq_u32 s41, 2
	s_cbranch_scc0 .Lea_n2_10
	v_pk_mul_f32 v[114:115], v[78:79], v[78:79]
	v_pk_fma_f32 v[114:115], v[80:81], v[80:81], v[114:115]
	v_pk_fma_f32 v[114:115], v[74:75], v[74:75], v[114:115]
	v_pk_fma_f32 v[114:115], v[76:77], v[76:77], v[114:115]
	v_pk_fma_f32 v[114:115], v[66:67], v[66:67], v[114:115]
	v_pk_fma_f32 v[114:115], v[68:69], v[68:69], v[114:115]
	v_pk_fma_f32 v[114:115], v[58:59], v[58:59], v[114:115]
	v_pk_fma_f32 v[114:115], v[60:61], v[60:61], v[114:115]
	v_pk_mul_f32 v[116:117], v[70:71], v[70:71]
	v_pk_fma_f32 v[116:117], v[72:73], v[72:73], v[116:117]
	v_pk_fma_f32 v[116:117], v[62:63], v[62:63], v[116:117]
	v_pk_fma_f32 v[116:117], v[64:65], v[64:65], v[116:117]
	v_pk_fma_f32 v[116:117], v[54:55], v[54:55], v[116:117]
	v_pk_fma_f32 v[116:117], v[56:57], v[56:57], v[116:117]
	v_pk_fma_f32 v[116:117], v[50:51], v[50:51], v[116:117]
	v_pk_fma_f32 v[116:117], v[52:53], v[52:53], v[116:117]
	v_add_f32_e32 v114, v114, v115
	v_add_f32_e32 v116, v116, v117
	v_mov_b32_e32 v118, v114
	v_mov_b32_e32 v119, v116
	s_nop 1
	v_permlane16_swap_b32 v114, v118
	v_permlane16_swap_b32 v116, v119
	v_add_f32_e32 v114, v114, v118
	v_add_f32_e32 v116, v116, v119
	s_nop 0
	v_mov_b32_e32 v118, v114
	v_mov_b32_e32 v119, v116
	s_nop 1
	v_permlane32_swap_b32 v114, v118
	v_permlane32_swap_b32 v116, v119
	v_add_f32_e32 v114, v114, v118
	v_add_f32_e32 v116, v116, v119
	s_nop 0
	v_mov_b32_e32 v120, 0x358637bd
	s_mov_b32 s2, 0x3c800000
	v_fma_f32 v114, v114, s2, v120
	v_fma_f32 v116, v116, s2, v120
	v_mul_f32_e32 v118, 0x4b800000, v114
	v_cmp_gt_f32_e32 vcc, s3, v114
	s_nop 1
	v_cndmask_b32_e32 v118, v114, v118, vcc
	v_rsq_f32_e32 v118, v118
	s_nop 0
	v_mul_f32_e32 v122, 0x45800000, v118
	v_cndmask_b32_e32 v122, v118, v122, vcc
	v_mul_f32_e32 v119, 0x4b800000, v116
	v_cmp_gt_f32_e32 vcc, s3, v116
	s_nop 1
	v_cndmask_b32_e32 v119, v116, v119, vcc
	v_rsq_f32_e32 v119, v119
	s_nop 0
	v_mul_f32_e32 v124, 0x45800000, v119
	v_cndmask_b32_e32 v124, v119, v124, vcc
	v_mul_f32_e32 v122, s43, v122
	v_mul_f32_e32 v124, s43, v124
	v_pk_mul_f32 v[126:127], v[194:195], v[122:123] op_sel_hi:[1,0]
	v_pk_mul_f32 v[78:79], v[78:79], v[126:127]
	v_pk_mul_f32 v[126:127], v[196:197], v[122:123] op_sel_hi:[1,0]
	v_pk_mul_f32 v[80:81], v[80:81], v[126:127]
	v_pk_mul_f32 v[126:127], v[198:199], v[122:123] op_sel_hi:[1,0]
	v_pk_mul_f32 v[74:75], v[74:75], v[126:127]
	v_pk_mul_f32 v[126:127], v[200:201], v[122:123] op_sel_hi:[1,0]
	v_pk_mul_f32 v[76:77], v[76:77], v[126:127]
	v_pk_mul_f32 v[126:127], v[202:203], v[122:123] op_sel_hi:[1,0]
	v_pk_mul_f32 v[66:67], v[66:67], v[126:127]
	v_pk_mul_f32 v[126:127], v[204:205], v[122:123] op_sel_hi:[1,0]
	v_pk_mul_f32 v[68:69], v[68:69], v[126:127]
	v_pk_mul_f32 v[126:127], v[206:207], v[122:123] op_sel_hi:[1,0]
	v_pk_mul_f32 v[58:59], v[58:59], v[126:127]
	v_pk_mul_f32 v[126:127], v[208:209], v[122:123] op_sel_hi:[1,0]
	v_pk_mul_f32 v[60:61], v[60:61], v[126:127]
	v_pk_mul_f32 v[126:127], v[194:195], v[124:125] op_sel_hi:[1,0]
	v_pk_mul_f32 v[70:71], v[70:71], v[126:127]
	v_pk_mul_f32 v[126:127], v[196:197], v[124:125] op_sel_hi:[1,0]
	v_pk_mul_f32 v[72:73], v[72:73], v[126:127]
	v_pk_mul_f32 v[126:127], v[198:199], v[124:125] op_sel_hi:[1,0]
	v_pk_mul_f32 v[62:63], v[62:63], v[126:127]
	v_pk_mul_f32 v[126:127], v[200:201], v[124:125] op_sel_hi:[1,0]
	v_pk_mul_f32 v[64:65], v[64:65], v[126:127]
	v_pk_mul_f32 v[126:127], v[202:203], v[124:125] op_sel_hi:[1,0]
	v_pk_mul_f32 v[54:55], v[54:55], v[126:127]
	v_pk_mul_f32 v[126:127], v[204:205], v[124:125] op_sel_hi:[1,0]
	v_pk_mul_f32 v[56:57], v[56:57], v[126:127]
	v_pk_mul_f32 v[126:127], v[206:207], v[124:125] op_sel_hi:[1,0]
	v_pk_mul_f32 v[50:51], v[50:51], v[126:127]
	v_pk_mul_f32 v[126:127], v[208:209], v[124:125] op_sel_hi:[1,0]
	v_pk_mul_f32 v[52:53], v[52:53], v[126:127]
	s_cmp_eq_u32 s42, 0
	s_cbranch_scc1 .Lea_pack_10
	s_waitcnt vmcnt(0)
	v_mul_f32_e32 v126, v74, v211
	v_mul_f32_e32 v127, v78, v211
	v_fma_f32 v78, v78, v210, -v126
	v_fma_f32 v74, v74, v210, v127
	v_mul_f32_e32 v126, v75, v213
	v_mul_f32_e32 v127, v79, v213
	v_fma_f32 v79, v79, v212, -v126
	v_fma_f32 v75, v75, v212, v127
	v_mul_f32_e32 v126, v76, v215
	v_mul_f32_e32 v127, v80, v215
	v_fma_f32 v80, v80, v214, -v126
	v_fma_f32 v76, v76, v214, v127
	v_mul_f32_e32 v126, v77, v217
	v_mul_f32_e32 v127, v81, v217
	v_fma_f32 v81, v81, v216, -v126
	v_fma_f32 v77, v77, v216, v127
	v_mul_f32_e32 v126, v58, v227
	v_mul_f32_e32 v127, v66, v227
	v_fma_f32 v66, v66, v226, -v126
	v_fma_f32 v58, v58, v226, v127
	v_mul_f32_e32 v126, v59, v229
	v_mul_f32_e32 v127, v67, v229
	v_fma_f32 v67, v67, v228, -v126
	v_fma_f32 v59, v59, v228, v127
	v_mul_f32_e32 v126, v60, v231
	v_mul_f32_e32 v127, v68, v231
	v_fma_f32 v68, v68, v230, -v126
	v_fma_f32 v60, v60, v230, v127
	v_mul_f32_e32 v126, v61, v233
	v_mul_f32_e32 v127, v69, v233
	v_fma_f32 v69, v69, v232, -v126
	v_fma_f32 v61, v61, v232, v127
	v_mul_f32_e32 v126, v62, v211
	v_mul_f32_e32 v127, v70, v211
	v_fma_f32 v70, v70, v210, -v126
	v_fma_f32 v62, v62, v210, v127
	v_mul_f32_e32 v126, v63, v213
	v_mul_f32_e32 v127, v71, v213
	v_fma_f32 v71, v71, v212, -v126
	v_fma_f32 v63, v63, v212, v127
	v_mul_f32_e32 v126, v64, v215
	v_mul_f32_e32 v127, v72, v215
	v_fma_f32 v72, v72, v214, -v126
	v_fma_f32 v64, v64, v214, v127
	v_mul_f32_e32 v126, v65, v217
	v_mul_f32_e32 v127, v73, v217
	v_fma_f32 v73, v73, v216, -v126
	v_fma_f32 v65, v65, v216, v127
	v_mul_f32_e32 v126, v50, v235
	v_mul_f32_e32 v127, v54, v235
	v_fma_f32 v54, v54, v234, -v126
	v_fma_f32 v50, v50, v234, v127
	v_mul_f32_e32 v126, v51, v237
	v_mul_f32_e32 v127, v55, v237
	v_fma_f32 v55, v55, v236, -v126
	v_fma_f32 v51, v51, v236, v127
	v_mul_f32_e32 v126, v52, v243
	v_mul_f32_e32 v127, v56, v243
	v_fma_f32 v56, v56, v242, -v126
	v_fma_f32 v52, v52, v242, v127
	v_mul_f32_e32 v126, v53, v245
	v_mul_f32_e32 v127, v57, v245
	v_fma_f32 v57, v57, v244, -v126
	v_fma_f32 v53, v53, v244, v127
	s_branch .Lea_pack_10

; DI void phaseA_tile(const Params& p0, int l, int ft, int mt, char* lds) {
;     ...
;         for (int n = 0; n < 2; ++n) {
;           float ss = 0.f;
; #pragma unroll
;           for (int m = 0; m < 4; ++m)
; #pragma unroll
;             for (int j = 0; j < 4; ++j) ss += v[n][m][j] * v[n][m][j];
;           ss += __shfl_xor(ss, 16);
;           ss += __shfl_xor(ss, 32);
;           const float rn = rsqrtf(ss * (1.f / 64.f) + EPS) * sc;
; #pragma unroll
;           for (int m = 0; m < 4; ++m)
; #pragma unroll
;             for (int j = 0; j < 4; ++j) v[n][m][j] *= rn * gv[m][j];
;         }
;         if (do_rope) {
; #pragma unroll
;           for (int n = 0; n < 2; ++n) {
;             f32x4 cs4[2][2];
;             const int s = s_base + tl[gp * 2 + n];
; #pragma unroll
;             for (int hf = 0; hf < 2; ++hf) {
;               const int pos = hf == 0 ? (s >> 6) : (s & 63);
;               const float* tb = p.rope + (size_t)pos * 32 + fq * 8;
;               cs4[hf][0] = *(const f32x4*)(tb);
;               cs4[hf][1] = *(const f32x4*)(tb + 4);
;             }
; #pragma unroll
;             for (int hf = 0; hf < 2; ++hf)
; #pragma unroll
;               for (int j = 0; j < 4; ++j) {
;                 const float c = cs4[hf][j >> 1][(j & 1) * 2], sn = cs4[hf][j >> 1][(j & 1) * 2 + 1];
;                 const float x1 = v[n][2 * hf][j], x2 = v[n][2 * hf + 1][j];
;                 v[n][2 * hf][j] = x1 * c - x2 * sn;
;                 v[n][2 * hf + 1][j] = x2 * c + x1 * sn;
;               }
;           }
;         }
.Lea_n1_01:
	s_cmp_eq_u32 s40, 2
	s_cbranch_scc0 .Lea_n2_01
	v_pk_mul_f32 v[114:115], v[110:111], v[110:111]
	v_pk_fma_f32 v[114:115], v[112:113], v[112:113], v[114:115]
	v_pk_fma_f32 v[114:115], v[106:107], v[106:107], v[114:115]
	v_pk_fma_f32 v[114:115], v[108:109], v[108:109], v[114:115]
	v_pk_fma_f32 v[114:115], v[98:99], v[98:99], v[114:115]
	v_pk_fma_f32 v[114:115], v[100:101], v[100:101], v[114:115]
	v_pk_fma_f32 v[114:115], v[90:91], v[90:91], v[114:115]
	v_pk_fma_f32 v[114:115], v[92:93], v[92:93], v[114:115]
	v_pk_mul_f32 v[116:117], v[102:103], v[102:103]
	v_pk_fma_f32 v[116:117], v[104:105], v[104:105], v[116:117]
	v_pk_fma_f32 v[116:117], v[94:95], v[94:95], v[116:117]
	v_pk_fma_f32 v[116:117], v[96:97], v[96:97], v[116:117]
	v_pk_fma_f32 v[116:117], v[86:87], v[86:87], v[116:117]
	v_pk_fma_f32 v[116:117], v[88:89], v[88:89], v[116:117]
	v_pk_fma_f32 v[116:117], v[82:83], v[82:83], v[116:117]
	v_pk_fma_f32 v[116:117], v[84:85], v[84:85], v[116:117]
	v_add_f32_e32 v114, v114, v115
	v_add_f32_e32 v116, v116, v117
	v_mov_b32_e32 v118, v114
	v_mov_b32_e32 v119, v116
	s_nop 1
	v_permlane16_swap_b32 v114, v118
	v_permlane16_swap_b32 v116, v119
	v_add_f32_e32 v114, v114, v118
	v_add_f32_e32 v116, v116, v119
	s_nop 0
	v_mov_b32_e32 v118, v114
	v_mov_b32_e32 v119, v116
	s_nop 1
	v_permlane32_swap_b32 v114, v118
	v_permlane32_swap_b32 v116, v119
	v_add_f32_e32 v114, v114, v118
	v_add_f32_e32 v116, v116, v119
	s_nop 0
	v_mov_b32_e32 v120, 0x358637bd
	s_mov_b32 s2, 0x3c800000
	v_fma_f32 v114, v114, s2, v120
	v_fma_f32 v116, v116, s2, v120
	v_mul_f32_e32 v118, 0x4b800000, v114
	v_cmp_gt_f32_e32 vcc, s3, v114
	s_nop 1
	v_cndmask_b32_e32 v118, v114, v118, vcc
	v_rsq_f32_e32 v118, v118
	s_nop 0
	v_mul_f32_e32 v122, 0x45800000, v118
	v_cndmask_b32_e32 v122, v118, v122, vcc
	v_mul_f32_e32 v119, 0x4b800000, v116
	v_cmp_gt_f32_e32 vcc, s3, v116
	s_nop 1
	v_cndmask_b32_e32 v119, v116, v119, vcc
	v_rsq_f32_e32 v119, v119
	s_nop 0
	v_mul_f32_e32 v124, 0x45800000, v119
	v_cndmask_b32_e32 v124, v119, v124, vcc
	v_mul_f32_e32 v122, s43, v122
	v_mul_f32_e32 v124, s43, v124
	v_pk_mul_f32 v[126:127], v[194:195], v[122:123] op_sel_hi:[1,0]
	v_pk_mul_f32 v[110:111], v[110:111], v[126:127]
	v_pk_mul_f32 v[126:127], v[196:197], v[122:123] op_sel_hi:[1,0]
	v_pk_mul_f32 v[112:113], v[112:113], v[126:127]
	v_pk_mul_f32 v[126:127], v[198:199], v[122:123] op_sel_hi:[1,0]
	v_pk_mul_f32 v[106:107], v[106:107], v[126:127]
	v_pk_mul_f32 v[126:127], v[200:201], v[122:123] op_sel_hi:[1,0]
	v_pk_mul_f32 v[108:109], v[108:109], v[126:127]
	v_pk_mul_f32 v[126:127], v[202:203], v[122:123] op_sel_hi:[1,0]
	v_pk_mul_f32 v[98:99], v[98:99], v[126:127]
	v_pk_mul_f32 v[126:127], v[204:205], v[122:123] op_sel_hi:[1,0]
	v_pk_mul_f32 v[100:101], v[100:101], v[126:127]
	v_pk_mul_f32 v[126:127], v[206:207], v[122:123] op_sel_hi:[1,0]
	v_pk_mul_f32 v[90:91], v[90:91], v[126:127]
	v_pk_mul_f32 v[126:127], v[208:209], v[122:123] op_sel_hi:[1,0]
	v_pk_mul_f32 v[92:93], v[92:93], v[126:127]
	v_pk_mul_f32 v[126:127], v[194:195], v[124:125] op_sel_hi:[1,0]
	v_pk_mul_f32 v[102:103], v[102:103], v[126:127]
	v_pk_mul_f32 v[126:127], v[196:197], v[124:125] op_sel_hi:[1,0]
	v_pk_mul_f32 v[104:105], v[104:105], v[126:127]
	v_pk_mul_f32 v[126:127], v[198:199], v[124:125] op_sel_hi:[1,0]
	v_pk_mul_f32 v[94:95], v[94:95], v[126:127]
	v_pk_mul_f32 v[126:127], v[200:201], v[124:125] op_sel_hi:[1,0]
	v_pk_mul_f32 v[96:97], v[96:97], v[126:127]
	v_pk_mul_f32 v[126:127], v[202:203], v[124:125] op_sel_hi:[1,0]
	v_pk_mul_f32 v[86:87], v[86:87], v[126:127]
	v_pk_mul_f32 v[126:127], v[204:205], v[124:125] op_sel_hi:[1,0]
	v_pk_mul_f32 v[88:89], v[88:89], v[126:127]
	v_pk_mul_f32 v[126:127], v[206:207], v[124:125] op_sel_hi:[1,0]
	v_pk_mul_f32 v[82:83], v[82:83], v[126:127]
	v_pk_mul_f32 v[126:127], v[208:209], v[124:125] op_sel_hi:[1,0]
	v_pk_mul_f32 v[84:85], v[84:85], v[126:127]
	s_cmp_eq_u32 s42, 0
	s_cbranch_scc1 .Lea_pack_01
	s_waitcnt vmcnt(0)
	v_mul_f32_e32 v126, v106, v219
	v_mul_f32_e32 v127, v110, v219
	v_fma_f32 v110, v110, v218, -v126
	v_fma_f32 v106, v106, v218, v127
	v_mul_f32_e32 v126, v107, v221
	v_mul_f32_e32 v127, v111, v221
	v_fma_f32 v111, v111, v220, -v126
	v_fma_f32 v107, v107, v220, v127
	v_mul_f32_e32 v126, v108, v223
	v_mul_f32_e32 v127, v112, v223
	v_fma_f32 v112, v112, v222, -v126
	v_fma_f32 v108, v108, v222, v127
	v_mul_f32_e32 v126, v109, v225
	v_mul_f32_e32 v127, v113, v225
	v_fma_f32 v113, v113, v224, -v126
	v_fma_f32 v109, v109, v224, v127
	v_mul_f32_e32 v126, v90, v227
	v_mul_f32_e32 v127, v98, v227
	v_fma_f32 v98, v98, v226, -v126
	v_fma_f32 v90, v90, v226, v127
	v_mul_f32_e32 v126, v91, v229
	v_mul_f32_e32 v127, v99, v229
	v_fma_f32 v99, v99, v228, -v126
	v_fma_f32 v91, v91, v228, v127
	v_mul_f32_e32 v126, v92, v231
	v_mul_f32_e32 v127, v100, v231
	v_fma_f32 v100, v100, v230, -v126
	v_fma_f32 v92, v92, v230, v127
	v_mul_f32_e32 v126, v93, v233
	v_mul_f32_e32 v127, v101, v233
	v_fma_f32 v101, v101, v232, -v126
	v_fma_f32 v93, v93, v232, v127
	v_mul_f32_e32 v126, v94, v219
	v_mul_f32_e32 v127, v102, v219
	v_fma_f32 v102, v102, v218, -v126
	v_fma_f32 v94, v94, v218, v127
	v_mul_f32_e32 v126, v95, v221
	v_mul_f32_e32 v127, v103, v221
	v_fma_f32 v103, v103, v220, -v126
	v_fma_f32 v95, v95, v220, v127
	v_mul_f32_e32 v126, v96, v223
	v_mul_f32_e32 v127, v104, v223
	v_fma_f32 v104, v104, v222, -v126
	v_fma_f32 v96, v96, v222, v127
	v_mul_f32_e32 v126, v97, v225
	v_mul_f32_e32 v127, v105, v225
	v_fma_f32 v105, v105, v224, -v126
	v_fma_f32 v97, v97, v224, v127
	v_mul_f32_e32 v126, v82, v235
	v_mul_f32_e32 v127, v86, v235
	v_fma_f32 v86, v86, v234, -v126
	v_fma_f32 v82, v82, v234, v127
	v_mul_f32_e32 v126, v83, v237
	v_mul_f32_e32 v127, v87, v237
	v_fma_f32 v87, v87, v236, -v126
	v_fma_f32 v83, v83, v236, v127
	v_mul_f32_e32 v126, v84, v243
	v_mul_f32_e32 v127, v88, v243
	v_fma_f32 v88, v88, v242, -v126
	v_fma_f32 v84, v84, v242, v127
	v_mul_f32_e32 v126, v85, v245
	v_mul_f32_e32 v127, v89, v245
	v_fma_f32 v89, v89, v244, -v126
	v_fma_f32 v85, v85, v244, v127
	s_branch .Lea_pack_01

; DI void phaseA_tile(const Params& p0, int l, int ft, int mt, char* lds) {
;     ...
;         for (int n = 0; n < 2; ++n) {
;           float ss = 0.f;
; #pragma unroll
;           for (int m = 0; m < 4; ++m)
; #pragma unroll
;             for (int j = 0; j < 4; ++j) ss += v[n][m][j] * v[n][m][j];
;           ss += __shfl_xor(ss, 16);
;           ss += __shfl_xor(ss, 32);
;           const float rn = rsqrtf(ss * (1.f / 64.f) + EPS) * sc;
; #pragma unroll
;           for (int m = 0; m < 4; ++m)
; #pragma unroll
;             for (int j = 0; j < 4; ++j) v[n][m][j] *= rn * gv[m][j];
;         }
;         if (do_rope) {
; #pragma unroll
;           for (int n = 0; n < 2; ++n) {
;             f32x4 cs4[2][2];
;             const int s = s_base + tl[gp * 2 + n];
; #pragma unroll
;             for (int hf = 0; hf < 2; ++hf) {
;               const int pos = hf == 0 ? (s >> 6) : (s & 63);
;               const float* tb = p.rope + (size_t)pos * 32 + fq * 8;
;               cs4[hf][0] = *(const f32x4*)(tb);
;               cs4[hf][1] = *(const f32x4*)(tb + 4);
;             }
; #pragma unroll
;             for (int hf = 0; hf < 2; ++hf)
; #pragma unroll
;               for (int j = 0; j < 4; ++j) {
;                 const float c = cs4[hf][j >> 1][(j & 1) * 2], sn = cs4[hf][j >> 1][(j & 1) * 2 + 1];
;                 const float x1 = v[n][2 * hf][j], x2 = v[n][2 * hf + 1][j];
;                 v[n][2 * hf][j] = x1 * c - x2 * sn;
;                 v[n][2 * hf + 1][j] = x2 * c + x1 * sn;
;               }
;           }
;         }
.Lea_n1_11:
	s_cmp_eq_u32 s41, 2
	s_cbranch_scc0 .Lea_n2_11
	v_pk_mul_f32 v[114:115], v[30:31], v[30:31]
	v_pk_fma_f32 v[114:115], v[32:33], v[32:33], v[114:115]
	v_pk_fma_f32 v[114:115], v[26:27], v[26:27], v[114:115]
	v_pk_fma_f32 v[114:115], v[28:29], v[28:29], v[114:115]
	v_pk_fma_f32 v[114:115], v[18:19], v[18:19], v[114:115]
	v_pk_fma_f32 v[114:115], v[20:21], v[20:21], v[114:115]
	v_pk_fma_f32 v[114:115], v[10:11], v[10:11], v[114:115]
	v_pk_fma_f32 v[114:115], v[12:13], v[12:13], v[114:115]
	v_pk_mul_f32 v[116:117], v[22:23], v[22:23]
	v_pk_fma_f32 v[116:117], v[24:25], v[24:25], v[116:117]
	v_pk_fma_f32 v[116:117], v[14:15], v[14:15], v[116:117]
	v_pk_fma_f32 v[116:117], v[16:17], v[16:17], v[116:117]
	v_pk_fma_f32 v[116:117], v[6:7], v[6:7], v[116:117]
	v_pk_fma_f32 v[116:117], v[8:9], v[8:9], v[116:117]
	v_pk_fma_f32 v[116:117], v[2:3], v[2:3], v[116:117]
	v_pk_fma_f32 v[116:117], v[4:5], v[4:5], v[116:117]
	v_add_f32_e32 v114, v114, v115
	v_add_f32_e32 v116, v116, v117
	v_mov_b32_e32 v118, v114
	v_mov_b32_e32 v119, v116
	s_nop 1
	v_permlane16_swap_b32 v114, v118
	v_permlane16_swap_b32 v116, v119
	v_add_f32_e32 v114, v114, v118
	v_add_f32_e32 v116, v116, v119
	s_nop 0
	v_mov_b32_e32 v118, v114
	v_mov_b32_e32 v119, v116
	s_nop 1
	v_permlane32_swap_b32 v114, v118
	v_permlane32_swap_b32 v116, v119
	v_add_f32_e32 v114, v114, v118
	v_add_f32_e32 v116, v116, v119
	s_nop 0
	v_mov_b32_e32 v120, 0x358637bd
	s_mov_b32 s2, 0x3c800000
	v_fma_f32 v114, v114, s2, v120
	v_fma_f32 v116, v116, s2, v120
	v_mul_f32_e32 v118, 0x4b800000, v114
	v_cmp_gt_f32_e32 vcc, s3, v114
	s_nop 1
	v_cndmask_b32_e32 v118, v114, v118, vcc
	v_rsq_f32_e32 v118, v118
	s_nop 0
	v_mul_f32_e32 v122, 0x45800000, v118
	v_cndmask_b32_e32 v122, v118, v122, vcc
	v_mul_f32_e32 v119, 0x4b800000, v116
	v_cmp_gt_f32_e32 vcc, s3, v116
	s_nop 1
	v_cndmask_b32_e32 v119, v116, v119, vcc
	v_rsq_f32_e32 v119, v119
	s_nop 0
	v_mul_f32_e32 v124, 0x45800000, v119
	v_cndmask_b32_e32 v124, v119, v124, vcc
	v_mul_f32_e32 v122, s43, v122
	v_mul_f32_e32 v124, s43, v124
	v_pk_mul_f32 v[126:127], v[194:195], v[122:123] op_sel_hi:[1,0]
	v_pk_mul_f32 v[30:31], v[30:31], v[126:127]
	v_pk_mul_f32 v[126:127], v[196:197], v[122:123] op_sel_hi:[1,0]
	v_pk_mul_f32 v[32:33], v[32:33], v[126:127]
	v_pk_mul_f32 v[126:127], v[198:199], v[122:123] op_sel_hi:[1,0]
	v_pk_mul_f32 v[26:27], v[26:27], v[126:127]
	v_pk_mul_f32 v[126:127], v[200:201], v[122:123] op_sel_hi:[1,0]
	v_pk_mul_f32 v[28:29], v[28:29], v[126:127]
	v_pk_mul_f32 v[126:127], v[202:203], v[122:123] op_sel_hi:[1,0]
	v_pk_mul_f32 v[18:19], v[18:19], v[126:127]
	v_pk_mul_f32 v[126:127], v[204:205], v[122:123] op_sel_hi:[1,0]
	v_pk_mul_f32 v[20:21], v[20:21], v[126:127]
	v_pk_mul_f32 v[126:127], v[206:207], v[122:123] op_sel_hi:[1,0]
	v_pk_mul_f32 v[10:11], v[10:11], v[126:127]
	v_pk_mul_f32 v[126:127], v[208:209], v[122:123] op_sel_hi:[1,0]
	v_pk_mul_f32 v[12:13], v[12:13], v[126:127]
	v_pk_mul_f32 v[126:127], v[194:195], v[124:125] op_sel_hi:[1,0]
	v_pk_mul_f32 v[22:23], v[22:23], v[126:127]
	v_pk_mul_f32 v[126:127], v[196:197], v[124:125] op_sel_hi:[1,0]
	v_pk_mul_f32 v[24:25], v[24:25], v[126:127]
	v_pk_mul_f32 v[126:127], v[198:199], v[124:125] op_sel_hi:[1,0]
	v_pk_mul_f32 v[14:15], v[14:15], v[126:127]
	v_pk_mul_f32 v[126:127], v[200:201], v[124:125] op_sel_hi:[1,0]
	v_pk_mul_f32 v[16:17], v[16:17], v[126:127]
	v_pk_mul_f32 v[126:127], v[202:203], v[124:125] op_sel_hi:[1,0]
	v_pk_mul_f32 v[6:7], v[6:7], v[126:127]
	v_pk_mul_f32 v[126:127], v[204:205], v[124:125] op_sel_hi:[1,0]
	v_pk_mul_f32 v[8:9], v[8:9], v[126:127]
	v_pk_mul_f32 v[126:127], v[206:207], v[124:125] op_sel_hi:[1,0]
	v_pk_mul_f32 v[2:3], v[2:3], v[126:127]
	v_pk_mul_f32 v[126:127], v[208:209], v[124:125] op_sel_hi:[1,0]
	v_pk_mul_f32 v[4:5], v[4:5], v[126:127]
	s_cmp_eq_u32 s42, 0
	s_cbranch_scc1 .Lea_pack_11
	s_waitcnt vmcnt(0)
	v_mul_f32_e32 v126, v26, v219
	v_mul_f32_e32 v127, v30, v219
	v_fma_f32 v30, v30, v218, -v126
	v_fma_f32 v26, v26, v218, v127
	v_mul_f32_e32 v126, v27, v221
	v_mul_f32_e32 v127, v31, v221
	v_fma_f32 v31, v31, v220, -v126
	v_fma_f32 v27, v27, v220, v127
	v_mul_f32_e32 v126, v28, v223
	v_mul_f32_e32 v127, v32, v223
	v_fma_f32 v32, v32, v222, -v126
	v_fma_f32 v28, v28, v222, v127
	v_mul_f32_e32 v126, v29, v225
	v_mul_f32_e32 v127, v33, v225
	v_fma_f32 v33, v33, v224, -v126
	v_fma_f32 v29, v29, v224, v127
	v_mul_f32_e32 v126, v10, v227
	v_mul_f32_e32 v127, v18, v227
	v_fma_f32 v18, v18, v226, -v126
	v_fma_f32 v10, v10, v226, v127
	v_mul_f32_e32 v126, v11, v229
	v_mul_f32_e32 v127, v19, v229
	v_fma_f32 v19, v19, v228, -v126
	v_fma_f32 v11, v11, v228, v127
	v_mul_f32_e32 v126, v12, v231
	v_mul_f32_e32 v127, v20, v231
	v_fma_f32 v20, v20, v230, -v126
	v_fma_f32 v12, v12, v230, v127
	v_mul_f32_e32 v126, v13, v233
	v_mul_f32_e32 v127, v21, v233
	v_fma_f32 v21, v21, v232, -v126
	v_fma_f32 v13, v13, v232, v127
	v_mul_f32_e32 v126, v14, v219
	v_mul_f32_e32 v127, v22, v219
	v_fma_f32 v22, v22, v218, -v126
	v_fma_f32 v14, v14, v218, v127
	v_mul_f32_e32 v126, v15, v221
	v_mul_f32_e32 v127, v23, v221
	v_fma_f32 v23, v23, v220, -v126
	v_fma_f32 v15, v15, v220, v127
	v_mul_f32_e32 v126, v16, v223
	v_mul_f32_e32 v127, v24, v223
	v_fma_f32 v24, v24, v222, -v126
	v_fma_f32 v16, v16, v222, v127
	v_mul_f32_e32 v126, v17, v225
	v_mul_f32_e32 v127, v25, v225
	v_fma_f32 v25, v25, v224, -v126
	v_fma_f32 v17, v17, v224, v127
	v_mul_f32_e32 v126, v2, v235
	v_mul_f32_e32 v127, v6, v235
	v_fma_f32 v6, v6, v234, -v126
	v_fma_f32 v2, v2, v234, v127
	v_mul_f32_e32 v126, v3, v237
	v_mul_f32_e32 v127, v7, v237
	v_fma_f32 v7, v7, v236, -v126
	v_fma_f32 v3, v3, v236, v127
	v_mul_f32_e32 v126, v4, v243
	v_mul_f32_e32 v127, v8, v243
	v_fma_f32 v8, v8, v242, -v126
	v_fma_f32 v4, v4, v242, v127
	v_mul_f32_e32 v126, v5, v245
	v_mul_f32_e32 v127, v9, v245
	v_fma_f32 v9, v9, v244, -v126
	v_fma_f32 v5, v5, v244, v127
	s_branch .Lea_pack_11
